# v46 + attention exp-section packed sub/mul + ret_sample wave_sum via permlane/DPP
# baseline (speedup 1.0000x reference)
; DEV bf16_t f2bf(float f) { return (bf16_t)(cvt_pk_bf16(f, 0.f) & 0xffffu); }
; DEV float bf2f(unsigned h) { return __uint_as_float(h << 16); }
; DEV float sigmoidf_(float x) { return 1.0f / (1.0f + __expf(-x)); }
; DEV void ret_sample_item(const Params& p, int l, int item, unsigned char* smem) {
;     ...
;   {
;     const int i = w;
;     const float qd = __expf(lg * (float)(i + 1));
;     float o[2]; float ss = 0.f;
; #pragma unroll
;     for (int c = 0; c < 2; ++c) {
;       const int e = lane + c * 64;
;       float a = qd * (part[(0 * 8 + i) * 128 + e] + part[(1 * 8 + i) * 128 + e] + part[(2 * 8 + i) * 128 + e] + part[(3 * 8 + i) * 128 + e]);
;       for (int j = 0; j <= i; ++j) a += inn[i * 8 + j] * vs[j * 128 + e];
;       o[c] = a; ss += a * a;
;     }
;     ss = wave_sum(ss);
;     const float rstd = rsqrtf(ss * (1.0f / 128.0f) + 1e-6f);
; #pragma unroll
;     for (int c = 0; c < 2; ++c) {
;       bf16_t* zp = Z + (rowbase + i) * NIN + RG + h * 128 + lane + c * 64;
;       const float g = bf2f(*zp);
;       *zp = f2bf(g * sigmoidf_(g) * o[c] * rstd);
.LBB0_335:
	s_or_b64 exec, exec, s[0:1]
	v_pk_mul_f32 v[2:3], v[0:1], v[0:1]
	s_nop 0
	v_add_f32_e32 v2, v2, v3
	s_mov_b32 s0, 0x800000
	s_lshl_b32 s6, s6, 1
	v_lshl_add_u64 v[106:107], v[64:65], 0, s[6:7]
	v_lshl_add_u64 v[106:107], v[106:107], 0, v[168:169]
	s_cmp_eq_u32 s12, s74
	s_cbranch_scc1 .Lrs_g1
	global_load_ushort v108, v[106:107], off offset:2048
	global_load_ushort v109, v[106:107], off offset:2176
	s_branch .Lrs_g1d

; DEV bf16_t f2bf(float f) { return (bf16_t)(cvt_pk_bf16(f, 0.f) & 0xffffu); }
; DEV float bf2f(unsigned h) { return __uint_as_float(h << 16); }
; DEV float sigmoidf_(float x) { return 1.0f / (1.0f + __expf(-x)); }
; DEV float wave_sum(float v) {
; #pragma unroll
;   for (int o = 32; o >= 1; o >>= 1) v += __shfl_xor(v, o);
;   return v;
; }
; DEV void ret_sample_item(const Params& p, int l, int item, unsigned char* smem) {
;     ...
;     ss = wave_sum(ss);
;     const float rstd = rsqrtf(ss * (1.0f / 128.0f) + 1e-6f);
; #pragma unroll
;     for (int c = 0; c < 2; ++c) {
;       bf16_t* zp = Z + (rowbase + i) * NIN + RG + h * 128 + lane + c * 64;
;       const float g = bf2f(*zp);
;       *zp = f2bf(g * sigmoidf_(g) * o[c] * rstd);
;     }
.Lrs_g1d:
	v_mov_b32_e32 v3, v2
	v_mov_b32_e32 v4, v2
	s_nop 1
	v_permlane32_swap_b32_e32 v3, v4
	s_nop 0
	v_add_f32_e32 v2, v3, v4
	s_nop 0
	v_mov_b32_e32 v3, v2
	v_mov_b32_e32 v4, v2
	s_nop 1
	v_permlane16_swap_b32_e32 v3, v4
	s_nop 0
	v_add_f32_e32 v2, v3, v4
	s_nop 1
	v_add_f32_dpp v2, v2, v2 row_ror:8 row_mask:0xf bank_mask:0xf
	s_nop 1
	v_mov_b32_dpp v3, v2 row_shl:4 row_mask:0xf bank_mask:0x5
	v_mov_b32_dpp v3, v2 row_shr:4 row_mask:0xf bank_mask:0xa
	s_nop 1
	v_add_f32_e32 v2, v2, v3
	s_nop 1
	v_add_f32_dpp v2, v2, v2 quad_perm:[2,3,0,1] row_mask:0xf bank_mask:0xf
	s_nop 1
	v_add_f32_dpp v2, v2, v2 quad_perm:[1,0,3,2] row_mask:0xf bank_mask:0xf
	s_nop 0
	v_fmamk_f32 v2, v2, 0x3c000000, v170
	v_cmp_gt_f32_e32 vcc, s0, v2
	v_mul_f32_e32 v3, 0x4b800000, v2
	s_nop 0
	v_cndmask_b32_e32 v2, v2, v3, vcc
	v_rsq_f32_e32 v2, v2
	s_nop 0
	v_mul_f32_e32 v3, 0x45800000, v2
	v_cndmask_b32_e32 v4, v2, v3, vcc
	s_waitcnt vmcnt(1)
	v_lshlrev_b32_e32 v5, 16, v108
	v_mul_f32_e32 v6, 0xbfb8aa3b, v5
	v_exp_f32_e32 v6, v6
	s_nop 0
	v_add_f32_e32 v6, 1.0, v6
	v_rcp_f32_e32 v8, v6
	s_nop 0
	v_fma_f32 v9, -v6, v8, 1.0
	v_fmac_f32_e32 v8, v9, v8
	v_mov_b32_e32 v6, v8
	v_mul_f32_e32 v5, v6, v5
	v_mul_f32_e32 v0, v0, v5
	v_mul_f32_e32 v0, v4, v0
	v_cvt_pk_bf16_f32 v0, v0, s0
	global_store_short v[106:107], v0, off offset:2048
	s_waitcnt vmcnt(1)
	v_lshlrev_b32_e32 v0, 16, v109
	v_mul_f32_e32 v5, 0xbfb8aa3b, v0
	v_exp_f32_e32 v5, v5
	s_nop 0
	v_add_f32_e32 v5, 1.0, v5
	v_rcp_f32_e32 v7, v5
	s_nop 0
	v_fma_f32 v8, -v5, v7, 1.0
	v_fmac_f32_e32 v7, v8, v7
	v_mov_b32_e32 v5, v7
	v_mul_f32_e32 v0, v5, v0
	v_mul_f32_e32 v0, v1, v0
	v_mul_f32_e32 v0, v4, v0
	v_cvt_pk_bf16_f32 v0, v0, s0
	global_store_short v[106:107], v0, off offset:2176
	s_barrier
